# stagger variant: P9 four groups (bit0 +1, bit3 +2 sleeps), P7/P10 two groups
# baseline (speedup 1.0000x reference)
.Lstg_p9_0:
	s_bitcmp1_b32 s54, 3
	s_cbranch_scc0 .Lstg_p9_1
	s_sleep 127
	s_sleep 127
